# attention loop: forget-bias folded into S MFMA C operand, packed exp-arg subtraction, max3 row max, SGPR-base K/V loads, precomputed V LDS bases
# speedup vs baseline: 1.1089x; 1.0089x over previous
; __device__ __forceinline__ void attn_block(const Params& P, int bh, int qb, unsigned char* smem) {
;     const int tid = opaque_tid(), lane = tid & 63, w = tid >> 6, g = lane >> 4, lr = lane & 15;
;     const int b = bh >> 3, h = bh & 7;
;     const bf16_t* z = (const bf16_t*)(P.ws + WS_Z);
;     const float* cum = (const float*)(P.ws + WS_CUM) + (size_t)bh * L;
;     int tq[2]; bool qvalid[2]; bf16x8 qf[2][2];
; #pragma unroll
;     for (int u = 0; u < 2; ++u) {
;         tq[u] = qb * 128 + 32 * w + 16 * u + lr;
;         qvalid[u] = tq[u] < L;
;         const bf16_t* qp = z + (size_t)(b * L + (qvalid[u] ? tq[u] : 0)) * NZ + ZC_FQ + h * 64 + 8 * g;
;         qf[u][0] = *(const bf16x8*)(qp); qf[u][1] = *(const bf16x8*)(qp + 32);
;     }
;     const int nkv = (2 * qb + 2 < 33) ? 2 * qb + 2 : 33;
;     const int srow0 = tid >> 3, sch = tid & 7;
;     uint4 rk0, rk1, rv0, rv1; float rc = 0.f;
;     auto load_tile = [&](int kv) {
;         const int key0 = kv * 64 + srow0, key1 = key0 + 32;
;         const bf16_t* p0 = z + (size_t)(b * L + (key0 < L ? key0 : L - 1)) * NZ + h * 64 + sch * 8;
;         const bf16_t* p1 = z + (size_t)(b * L + (key1 < L ? key1 : L - 1)) * NZ + h * 64 + sch * 8;
;         rk0 = *(const uint4*)(p0 + ZC_FK); rv0 = *(const uint4*)(p0 + ZC_FV);
;         rk1 = *(const uint4*)(p1 + ZC_FK); rv1 = *(const uint4*)(p1 + ZC_FV);
;         const int keyc = kv * 64 + (tid & 63);
;         rc = cum[keyc < L ? keyc : L - 1];
;     };
;     auto store_tile = [&](int buf) {
;         unsigned char* sK = smem + buf * 16384; unsigned char* sV = sK + 8192;
;         const int row0 = srow0, row1 = srow0 + 32;
;         *(uint4*)(sK + row0 * 128 + ((sch ^ (row0 & 7)) << 4)) = rk0;
;         *(uint4*)(sV + vimg_off(row0, sch)) = rv0;
;         *(uint4*)(sK + row1 * 128 + ((sch ^ (row1 & 7)) << 4)) = rk1;
;         *(uint4*)(sV + vimg_off(row1, sch)) = rv1;
;         if (tid < 64) ((float*)(smem + 32768 + buf * 256))[tid] = rc;
;     };
;     float m[2] = {-1e30f, -1e30f};
;     f32x4 o[2][5];
; #pragma unroll
;     for (int u = 0; u < 2; ++u)
; #pragma unroll
;         for (int c = 0; c < 5; ++c) o[u][c] = (f32x4){0.f, 0.f, 0.f, 0.f};
;     const unsigned onew = (lr == 0) ? 0x3F803F80u : 0u;
;     const bf16x8 vones = __builtin_bit_cast(bf16x8, make_uint4(onew, onew, onew, onew));
;     load_tile(nkv - 1); store_tile((nkv - 1) & 1);
.LBB0_705:
	s_add_i32 s10, s2, 0xfffffa40
	s_waitcnt lgkmcnt(1)
	v_mov_b32_e32 v5, v0
	s_lshr_b32 s0, s10, 6
	s_sub_i32 s12, 16, s0
	v_ashrrev_i32_e32 v2, 1, v5
	v_and_b32_e32 v2, 0xffffffe0, v2
	v_and_b32_e32 v169, 15, v5
	v_lshl_add_u32 v2, s12, 7, v2
	v_or_b32_e32 v168, v2, v169
	s_lshl_b32 s0, s2, 6
	s_and_b32 s6, s0, 0x1c0
	v_or_b32_e32 v135, 16, v168
	s_bfe_u32 s14, s2, 0x30003
	v_cmp_gt_i32_e64 s[8:9], s3, v168
	s_lshl_b32 s34, s6, 1
	v_cmp_gt_i32_e64 s[6:7], s3, v135
	s_mulk_i32 s14, 0x810
	v_cndmask_b32_e64 v2, 0, v168, s[8:9]
	v_cndmask_b32_e64 v16, 0, v135, s[6:7]
	v_add_u32_e32 v2, s14, v2
	v_mov_b64_e32 v[14:15], s[80:81]
	v_add_u32_e32 v16, s14, v16
	s_and_b32 s11, s2, 63
	v_mad_i64_i32 v[6:7], s[0:1], v2, s20, v[14:15]
	v_mad_i64_i32 v[16:17], s[0:1], v16, s20, v[14:15]
	s_lshl_b32 s15, s12, 1
	s_add_i32 s0, s15, 2
	s_mulk_i32 s11, 0x2040
	s_add_u32 s12, s71, s11
	v_readlane_b32 s1, v212, 15
	s_addc_u32 s13, s1, 0
	s_cmp_gt_u32 s10, 63
	s_cselect_b32 s43, s0, 33
	s_add_i32 s23, s43, -1
	s_waitcnt lgkmcnt(0)
	v_bfe_u32 v4, v5, 4, 2
	s_waitcnt vmcnt(4)
	v_ashrrev_i32_e32 v22, 3, v5
	s_lshl_b32 s68, s23, 6
	v_lshl_add_u64 v[6:7], v[6:7], 0, s[34:35]
	v_lshlrev_b32_e32 v2, 4, v4
	v_lshl_add_u64 v[16:17], v[16:17], 0, s[34:35]
	s_waitcnt vmcnt(3)
	v_add_u32_e32 v24, s68, v22
	v_lshl_add_u64 v[6:7], v[6:7], 0, v[2:3]
	v_lshl_add_u64 v[16:17], v[16:17], 0, v[2:3]
	v_min_i32_e32 v2, 0x80f, v24
	v_lshl_add_u64 v[10:11], v[6:7], 0, s[48:49]
	v_add_co_u32_e32 v6, vcc, s87, v6
	v_add_u32_e32 v2, s14, v2
	s_nop 0
	v_addc_co_u32_e32 v7, vcc, 0, v7, vcc
	v_and_b32_e32 v23, 7, v5
	v_mad_i64_i32 v[20:21], s[0:1], v2, s20, v[14:15]
	v_min_i32_e32 v24, 0x7ef, v24
	s_add_i32 s42, s14, 32
	v_lshl_add_u64 v[18:19], v[16:17], 0, s[48:49]
	v_add_co_u32_e32 v16, vcc, s87, v16
	v_lshl_add_u64 v[20:21], v[20:21], 0, s[34:35]
	v_lshlrev_b32_e32 v2, 4, v23
	v_add_u32_e32 v24, s42, v24
	v_addc_co_u32_e32 v17, vcc, 0, v17, vcc
	v_lshl_add_u64 v[20:21], v[20:21], 0, v[2:3]
	v_mad_i64_i32 v[14:15], s[0:1], v24, s20, v[14:15]
	v_lshl_add_u64 v[14:15], v[14:15], 0, s[34:35]
	v_add_co_u32_e32 v20, vcc, s87, v20
	v_lshl_add_u64 v[14:15], v[14:15], 0, v[2:3]
	s_nop 0
	v_addc_co_u32_e32 v21, vcc, 0, v21, vcc
	global_load_dwordx4 v[6:9], v[6:7], off
	s_nop 0
	global_load_dwordx4 v[10:13], v[10:11], off offset:64
	s_nop 0
	global_load_dwordx4 v[26:29], v[20:21], off offset:1024
	global_load_dwordx4 v[30:33], v[20:21], off offset:2048
	v_add_co_u32_e32 v14, vcc, s87, v14
	v_xor_b32_e32 v2, v22, v5
	s_nop 0
	v_addc_co_u32_e32 v15, vcc, 0, v15, vcc
	global_load_dwordx4 v[34:37], v[14:15], off offset:1024
	global_load_dwordx4 v[38:41], v[14:15], off offset:2048
	s_nop 0
	global_load_dwordx4 v[14:17], v[16:17], off
	s_nop 0
	global_load_dwordx4 v[18:21], v[18:19], off offset:64
	s_and_b32 s69, s23, 1
	v_lshlrev_b32_e32 v2, 4, v2
	s_lshl_b32 s0, s69, 14
	v_lshlrev_b32_e32 v170, 7, v22
	v_bitop3_b32 v25, v22, v23, 6 bitop3:0x6c
	v_and_b32_e32 v172, 0x70, v2
	s_add_i32 s70, s0, 0
	v_and_b32_e32 v24, 63, v5
	v_lshl_or_b32 v171, v25, 4, v170
	v_add3_u32 v2, s70, v170, v172
	v_cmp_gt_i32_e64 s[10:11], 64, v5
	v_add_u32_e32 v25, s70, v171
	s_waitcnt vmcnt(5)
	ds_write_b128 v2, v[26:29]
	s_waitcnt vmcnt(4)
	ds_write_b128 v25, v[30:33] offset:8192
	s_waitcnt vmcnt(3)
	ds_write_b128 v2, v[34:37] offset:4096
	s_waitcnt vmcnt(2)
	ds_write_b128 v25, v[38:41] offset:12288
	s_and_saveexec_b64 s[0:1], s[10:11]
	s_cbranch_execz .LBB0_707
	v_or_b32_e32 v2, s68, v24
	v_min_u32_e32 v2, 0x80f, v2
	v_lshlrev_b32_e32 v2, 2, v2
	global_load_dword v2, v2, s[12:13]
	s_mulk_i32 s69, 0xc100
	s_add_i32 s70, s70, s69
	v_lshl_add_u32 v25, v5, 2, s70
	s_waitcnt vmcnt(0)
	v_xor_b32_e32 v2, 0x80000000, v2
	ds_write_b32 v25, v2 offset:32768
.LBB0_707:
	s_or_b64 exec, exec, s[0:1]
	s_lshl_b32 s43, s43, 6
	s_add_i32 s68, s43, 0xffffff80
	v_add_u32_e32 v25, s68, v22
	v_min_i32_e32 v26, 0x80f, v25
	v_add_u32_e32 v28, s14, v26
	v_mov_b64_e32 v[26:27], s[80:81]
	v_lshlrev_b32_e32 v2, 3, v23
	v_mad_i64_i32 v[28:29], s[0:1], v28, s20, v[26:27]
	v_min_i32_e32 v25, 0x7ef, v25
	v_lshl_add_u64 v[28:29], v[28:29], 0, s[34:35]
	v_lshlrev_b32_e32 v2, 1, v2
	v_add_u32_e32 v25, s42, v25
	v_lshl_add_u64 v[28:29], v[28:29], 0, v[2:3]
	v_mad_i64_i32 v[26:27], s[0:1], v25, s20, v[26:27]
	v_lshl_add_u64 v[26:27], v[26:27], 0, s[34:35]
	v_add_co_u32_e32 v28, vcc, s87, v28
	v_lshl_add_u64 v[26:27], v[26:27], 0, v[2:3]
	s_nop 0
	v_addc_co_u32_e32 v29, vcc, 0, v29, vcc
	v_or_b32_e32 v25, s68, v24
	v_add_co_u32_e32 v26, vcc, s87, v26
	v_min_u32_e32 v25, 0x80f, v25
	s_nop 0
	v_addc_co_u32_e32 v27, vcc, 0, v27, vcc
	v_lshlrev_b32_e32 v25, 2, v25
	s_waitcnt lgkmcnt(0)
	s_barrier
; __device__ __forceinline__ unsigned cvt_pk_bf16(float lo, float hi) { f32x2 v = {lo, hi}; bf16x2v b = __builtin_convertvector(v, bf16x2v); return __builtin_bit_cast(unsigned, b); }
; __device__ __forceinline__ void attn_block(const Params& P, int bh, int qb, unsigned char* smem) {
;     ...
;     float m[2] = {-1e30f, -1e30f};
;     f32x4 o[2][5];
; #pragma unroll
;     for (int u = 0; u < 2; ++u)
; #pragma unroll
;         for (int c = 0; c < 5; ++c) o[u][c] = (f32x4){0.f, 0.f, 0.f, 0.f};
;     const unsigned onew = (lr == 0) ? 0x3F803F80u : 0u;
;     const bf16x8 vones = __builtin_bit_cast(bf16x8, make_uint4(onew, onew, onew, onew));
;     load_tile(nkv - 1); store_tile((nkv - 1) & 1);
;     __syncthreads();
;     if (nkv > 1) load_tile(nkv - 2);
;     ...
;             const float mn = m[u];
; #pragma unroll
;             for (int c = 0; c < 4; ++c)
; #pragma unroll
;                 for (int r = 0; r < 4; ++r) sa[u][c][r] = __builtin_amdgcn_exp2f(sa[u][c][r] - mn);
; #pragma unroll
;             for (int s2 = 0; s2 < 2; ++s2) {
;                 uint4 uu;
;                 uu.x = cvt_pk_bf16(sa[u][2 * s2][0], sa[u][2 * s2][1]); uu.y = cvt_pk_bf16(sa[u][2 * s2][2], sa[u][2 * s2][3]);
;                 uu.z = cvt_pk_bf16(sa[u][2 * s2 + 1][0], sa[u][2 * s2 + 1][1]); uu.w = cvt_pk_bf16(sa[u][2 * s2 + 1][2], sa[u][2 * s2 + 1][3]);
;                 pf[u][s2] = __builtin_bit_cast(bf16x8, uu);
;             }
;         }
;         {
;             uint2 vr[4][4];
;             tr_read_4c(sV, g, lr, vr);
; #pragma unroll
;             for (int c = 0; c < 4; ++c)
; #pragma unroll
;                 for (int s2 = 0; s2 < 2; ++s2) {
;                     const bf16x8 vf = tr_pair(vr[c][2 * s2], vr[c][2 * s2 + 1]);
;                     o[0][c] = __builtin_amdgcn_mfma_f32_16x16x32_bf16(vf, pf[0][s2], o[0][c], 0, 0, 0);
;                     o[1][c] = __builtin_amdgcn_mfma_f32_16x16x32_bf16(vf, pf[1][s2], o[1][c], 0, 0, 0);
;                 }
; #pragma unroll
;             for (int s2 = 0; s2 < 2; ++s2) {
;                 o[0][4] = __builtin_amdgcn_mfma_f32_16x16x32_bf16(vones, pf[0][s2], o[0][4], 0, 0, 0);
;                 o[1][4] = __builtin_amdgcn_mfma_f32_16x16x32_bf16(vones, pf[1][s2], o[1][4], 0, 0, 0);
;             }
;         }
	global_load_dwordx4 v[58:61], v[28:29], off offset:1024
	global_load_dwordx4 v[62:65], v[28:29], off offset:2048
	global_load_dwordx4 v[70:73], v[26:27], off offset:1024
	global_load_dwordx4 v[74:77], v[26:27], off offset:2048
	global_load_dword v179, v25, s[12:13]
	s_add_u32 s0, s80, s34
	s_addc_u32 s1, s81, 0
	v_lshl_add_u64 v[136:137], s[0:1], 0, v[2:3]
	v_lshlrev_b32_e32 v174, 2, v4
	v_lshrrev_b32_e32 v2, 2, v169
	v_or_b32_e32 v25, v174, v2
	v_bfe_u32 v27, v169, 1, 1
	v_bitop3_b32 v2, v174, 6, v2 bitop3:0xc8
	v_or_b32_e32 v2, v2, v27
	v_lshlrev_b32_e32 v177, 4, v2
	v_lshlrev_b32_e32 v2, 3, v169
	v_and_b32_e32 v138, 8, v2
	v_or_b32_e32 v2, 2, v27
	v_bitop3_b32 v2, v25, v2, 6 bitop3:0x6c
	v_lshlrev_b32_e32 v178, 4, v2
	v_or_b32_e32 v2, 4, v27
	v_lshrrev_b32_e32 v26, 1, v169
	v_bitop3_b32 v2, v25, v2, 6 bitop3:0x6c
	v_lshlrev_b32_e32 v180, 4, v2
	v_bitop3_b32 v2, v25, v26, 6 bitop3:0x4e
	v_lshlrev_b32_e32 v181, 4, v2
	v_xor_b32_e32 v2, v4, v23
	v_cmp_eq_u32_e32 vcc, 0, v169
	v_lshl_add_u32 v175, v4, 4, 0
	v_lshl_add_u32 v182, v5, 2, 0
	v_lshlrev_b32_e32 v183, 4, v2
	v_bitop3_b32 v2, v4, v23, 4 bitop3:0x36
	v_mov_b32_e32 v4, v3
	v_mov_b32_e32 v5, v3
	v_cndmask_b32_e32 v54, 0, v159, vcc
	v_lshlrev_b32_e32 v176, 7, v25
	v_lshlrev_b32_e32 v184, 4, v2
	v_or_b32_e32 v185, 0xffffff40, v24
	v_add_u32_e32 v186, 0xffffff40, v22
	v_mov_b32_e32 v2, v3
	v_mov_b64_e32 v[68:69], v[4:5]
	v_mov_b64_e32 v[52:53], v[4:5]
	v_mov_b64_e32 v[48:49], v[4:5]
	v_mov_b64_e32 v[44:45], v[4:5]
	v_mov_b64_e32 v[80:81], v[4:5]
	v_mov_b64_e32 v[36:37], v[4:5]
	v_mov_b64_e32 v[32:33], v[4:5]
	v_mov_b64_e32 v[28:29], v[4:5]
	v_mov_b64_e32 v[24:25], v[4:5]
	v_mov_b64_e32 v[40:41], v[4:5]
	v_mov_b32_e32 v55, v54
	v_mov_b32_e32 v56, v54
	v_mov_b32_e32 v57, v54
	v_lshlrev_b32_e32 v173, 7, v169
	v_mov_b32_e32 v187, 0xf149f2ca
	v_mov_b64_e32 v[66:67], v[2:3]
	v_mov_b64_e32 v[50:51], v[2:3]
	v_mov_b64_e32 v[46:47], v[2:3]
	v_mov_b64_e32 v[42:43], v[2:3]
	v_mov_b64_e32 v[78:79], v[2:3]
	v_mov_b64_e32 v[34:35], v[2:3]
	v_mov_b64_e32 v[30:31], v[2:3]
	v_mov_b64_e32 v[26:27], v[2:3]
	v_mov_b64_e32 v[22:23], v[2:3]
	v_mov_b64_e32 v[38:39], v[2:3]
	v_mov_b32_e32 v2, 0xf149f2ca
	v_mov_b32_e32 v196, 0x7149f2ca
	v_mov_b32_e32 v230, 0x7149f2ca
	v_add3_u32 v208, v177, v176, v138
	v_add3_u32 v209, v178, v176, v138
	v_add3_u32 v210, v180, v176, v138
	v_add3_u32 v211, v181, v176, v138
	v_add_u32_e32 v208, s84, v208
	v_add_u32_e32 v209, s84, v209
	v_add_u32_e32 v210, s84, v210
	v_add_u32_e32 v211, s84, v211
	v_lshlrev_b32_e32 v242, 2, v185
	v_add_u32_e32 v198, s43, v186
	v_add_u32_e32 v198, s14, v198
	v_mad_i64_i32 v[198:199], s[0:1], v198, s20, v[136:137]
	s_nop 1
	v_add_co_u32_e32 v198, vcc, 0x1000, v198
	s_nop 1
	v_addc_co_u32_e32 v199, vcc, 0, v199, vcc
	s_nop 1
	v_readfirstlane_b32 s98, v198
	v_readfirstlane_b32 s99, v199
	s_nop 1
	v_subrev_u32_e32 v198, s98, v198
	v_add_u32_e32 v199, 0x38000, v198
	s_branch .LBB0_709
.LBB0_708:
	v_pk_add_f32 v[102:103], v[102:103], v[196:197] op_sel_hi:[1,0]
	v_pk_add_f32 v[104:105], v[104:105], v[196:197] op_sel_hi:[1,0]
	v_pk_add_f32 v[98:99], v[98:99], v[196:197] op_sel_hi:[1,0]
	v_pk_add_f32 v[100:101], v[100:101], v[196:197] op_sel_hi:[1,0]
	v_pk_add_f32 v[110:111], v[110:111], v[196:197] op_sel_hi:[1,0]
	v_pk_add_f32 v[112:113], v[112:113], v[196:197] op_sel_hi:[1,0]
	v_pk_add_f32 v[106:107], v[106:107], v[196:197] op_sel_hi:[1,0]
	v_pk_add_f32 v[108:109], v[108:109], v[196:197] op_sel_hi:[1,0]
	v_exp_f32_e32 v102, v102
	v_exp_f32_e32 v103, v103
	v_exp_f32_e32 v104, v104
	v_exp_f32_e32 v105, v105
	v_exp_f32_e32 v98, v98
	v_exp_f32_e32 v99, v99
	v_exp_f32_e32 v100, v100
	v_exp_f32_e32 v101, v101
	v_exp_f32_e32 v110, v110
	v_exp_f32_e32 v111, v111
	v_exp_f32_e32 v112, v112
	v_exp_f32_e32 v113, v113
	v_exp_f32_e32 v106, v106
	v_exp_f32_e32 v107, v107
	v_exp_f32_e32 v108, v108
	v_exp_f32_e32 v109, v109
	v_cvt_pk_bf16_f32 v200, v102, v103
	v_cvt_pk_bf16_f32 v201, v104, v105
	v_cvt_pk_bf16_f32 v202, v98, v99
	v_cvt_pk_bf16_f32 v203, v100, v101
	v_cvt_pk_bf16_f32 v204, v110, v111
	v_cvt_pk_bf16_f32 v205, v112, v113
	v_cvt_pk_bf16_f32 v206, v106, v107
	v_cvt_pk_bf16_f32 v207, v108, v109
	v_add_u32_e32 v4, s68, v208
	v_add_u32_e32 v5, s68, v209
	v_add_u32_e32 v128, s68, v210
	v_add_u32_e32 v129, s68, v211
	ds_read_b64_tr_b16 v[188:189], v4
	ds_read_b64_tr_b16 v[190:191], v4 offset:2048
	ds_read_b64_tr_b16 v[124:125], v4 offset:4096
	ds_read_b64_tr_b16 v[126:127], v4 offset:6144
	ds_read_b64_tr_b16 v[120:121], v5
	ds_read_b64_tr_b16 v[122:123], v5 offset:2048
	ds_read_b64_tr_b16 v[116:117], v5 offset:4096
	ds_read_b64_tr_b16 v[118:119], v5 offset:6144
	ds_read_b64_tr_b16 v[112:113], v128
	ds_read_b64_tr_b16 v[114:115], v128 offset:2048
	ds_read_b64_tr_b16 v[108:109], v128 offset:4096
	ds_read_b64_tr_b16 v[110:111], v128 offset:6144
	ds_read_b64_tr_b16 v[104:105], v129
	ds_read_b64_tr_b16 v[106:107], v129 offset:2048
	ds_read_b64_tr_b16 v[100:101], v129 offset:4096
	ds_read_b64_tr_b16 v[102:103], v129 offset:6144
	v_pk_add_f32 v[86:87], v[86:87], v[230:231] op_sel_hi:[1,0]
	v_pk_add_f32 v[88:89], v[88:89], v[230:231] op_sel_hi:[1,0]
	v_pk_add_f32 v[82:83], v[82:83], v[230:231] op_sel_hi:[1,0]
	v_pk_add_f32 v[84:85], v[84:85], v[230:231] op_sel_hi:[1,0]
	v_pk_add_f32 v[94:95], v[94:95], v[230:231] op_sel_hi:[1,0]
	v_pk_add_f32 v[96:97], v[96:97], v[230:231] op_sel_hi:[1,0]
	v_pk_add_f32 v[90:91], v[90:91], v[230:231] op_sel_hi:[1,0]
	v_pk_add_f32 v[92:93], v[92:93], v[230:231] op_sel_hi:[1,0]
	v_exp_f32_e32 v86, v86
	v_exp_f32_e32 v87, v87
	v_exp_f32_e32 v88, v88
	v_exp_f32_e32 v89, v89
	v_exp_f32_e32 v82, v82
	v_exp_f32_e32 v83, v83
	v_exp_f32_e32 v84, v84
	v_exp_f32_e32 v85, v85
	v_exp_f32_e32 v94, v94
	v_exp_f32_e32 v95, v95
	v_exp_f32_e32 v96, v96
	v_exp_f32_e32 v97, v97
	v_exp_f32_e32 v90, v90
	v_exp_f32_e32 v91, v91
	v_exp_f32_e32 v92, v92
	v_exp_f32_e32 v93, v93
	v_cvt_pk_bf16_f32 v232, v86, v87
	v_cvt_pk_bf16_f32 v233, v88, v89
	v_cvt_pk_bf16_f32 v234, v82, v83
	v_cvt_pk_bf16_f32 v235, v84, v85
	v_cvt_pk_bf16_f32 v236, v94, v95
	v_cvt_pk_bf16_f32 v237, v96, v97
	v_cvt_pk_bf16_f32 v238, v90, v91
	v_cvt_pk_bf16_f32 v239, v92, v93
	s_waitcnt lgkmcnt(0)
	v_mfma_f32_16x16x32_bf16 v[66:69], v[188:191], v[200:203], v[66:69]
	s_add_i32 s23, s23, -1
	s_sub_i32 s43, s43, 64
	s_cmp_eq_u32 s23, -1
	v_mfma_f32_16x16x32_bf16 v[34:37], v[188:191], v[232:235], v[34:37]
	v_mfma_f32_16x16x32_bf16 v[50:53], v[120:123], v[200:203], v[50:53]
	s_barrier
; __device__ __forceinline__ void attn_block(const Params& P, int bh, int qb, unsigned char* smem) {
;     ...
;         const int buf = kv & 1;
;         const unsigned char* sK = smem + buf * 16384; const unsigned char* sV = sK + 8192;
;         const float* sck = (const float*)(smem + 32768 + buf * 256);
;         f32x4 sa[2][4];
; #pragma unroll
;         for (int c = 0; c < 4; ++c) {
;             sa[0][c] = (f32x4){0.f, 0.f, 0.f, 0.f}; sa[1][c] = (f32x4){0.f, 0.f, 0.f, 0.f};
; #pragma unroll
;             for (int s = 0; s < 2; ++s) {
;                 const bf16x8 kf = *(const bf16x8*)(sK + (16 * c + lr) * 128 + (((4 * s + g) ^ (lr & 7)) << 4));
;                 sa[0][c] = __builtin_amdgcn_mfma_f32_16x16x32_bf16(kf, qf[0][s], sa[0][c], 0, 0, 0);
;                 sa[1][c] = __builtin_amdgcn_mfma_f32_16x16x32_bf16(kf, qf[1][s], sa[1][c], 0, 0, 0);
;             }
;         }
;         __builtin_amdgcn_sched_barrier(0);
;         if (kv > 0) store_tile(buf ^ 1);
;     ...
;             for (int c = 0; c < 4; ++c)
; #pragma unroll
;                 for (int s2 = 0; s2 < 2; ++s2) {
;                     const bf16x8 vf = tr_pair(vr[c][2 * s2], vr[c][2 * s2 + 1]);
;                     o[0][c] = __builtin_amdgcn_mfma_f32_16x16x32_bf16(vf, pf[0][s2], o[0][c], 0, 0, 0);
;                     o[1][c] = __builtin_amdgcn_mfma_f32_16x16x32_bf16(vf, pf[1][s2], o[1][c], 0, 0, 0);
;                 }
; #pragma unroll
;             for (int s2 = 0; s2 < 2; ++s2) {
;                 o[0][4] = __builtin_amdgcn_mfma_f32_16x16x32_bf16(vones, pf[0][s2], o[0][4], 0, 0, 0);
;                 o[1][4] = __builtin_amdgcn_mfma_f32_16x16x32_bf16(vones, pf[1][s2], o[1][4], 0, 0, 0);
;             }
;         }
;         __syncthreads();
	v_mfma_f32_16x16x32_bf16 v[30:33], v[120:123], v[232:235], v[30:33]
	v_mfma_f32_16x16x32_bf16 v[46:49], v[112:115], v[200:203], v[46:49]
	v_mfma_f32_16x16x32_bf16 v[26:29], v[112:115], v[232:235], v[26:29]
	v_mfma_f32_16x16x32_bf16 v[42:45], v[104:107], v[200:203], v[42:45]
	v_mfma_f32_16x16x32_bf16 v[22:25], v[104:107], v[232:235], v[22:25]
	v_mfma_f32_16x16x32_bf16 v[78:81], v[54:57], v[200:203], v[78:81]
	v_mfma_f32_16x16x32_bf16 v[38:41], v[54:57], v[232:235], v[38:41]
	v_mfma_f32_16x16x32_bf16 v[66:69], v[124:127], v[204:207], v[66:69]
	v_mfma_f32_16x16x32_bf16 v[34:37], v[124:127], v[236:239], v[34:37]
	v_mfma_f32_16x16x32_bf16 v[50:53], v[116:119], v[204:207], v[50:53]
	v_mfma_f32_16x16x32_bf16 v[30:33], v[116:119], v[236:239], v[30:33]
	v_mfma_f32_16x16x32_bf16 v[46:49], v[108:111], v[204:207], v[46:49]
	v_mfma_f32_16x16x32_bf16 v[26:29], v[108:111], v[236:239], v[26:29]
	v_mfma_f32_16x16x32_bf16 v[42:45], v[100:103], v[204:207], v[42:45]
	v_mfma_f32_16x16x32_bf16 v[22:25], v[100:103], v[236:239], v[22:25]
	v_mfma_f32_16x16x32_bf16 v[78:81], v[54:57], v[204:207], v[78:81]
	v_mfma_f32_16x16x32_bf16 v[38:41], v[54:57], v[236:239], v[38:41]
	s_cbranch_scc1 .LBB0_721
.LBB0_709:
	s_and_b32 s69, s23, 1
	s_lshl_b32 s0, s69, 14
	s_add_i32 s68, s0, 0
	v_lshl_add_u32 v4, s69, 8, v175
	ds_read_b128 v[214:217], v4 offset:32768
	ds_read_b128 v[218:221], v4 offset:32832
	ds_read_b128 v[222:225], v4 offset:32896
	ds_read_b128 v[226:229], v4 offset:32960
	v_add_u32_e32 v4, s68, v173
	v_add_u32_e32 v5, v4, v183
	ds_read_b128 v[82:85], v5
	ds_read_b128 v[90:93], v5 offset:2048
	v_add_u32_e32 v4, v4, v184
	ds_read_b128 v[94:97], v4
	ds_read_b128 v[106:109], v4 offset:2048
	s_waitcnt lgkmcnt(3)
	v_mfma_f32_16x16x32_bf16 v[86:89], v[82:85], v[6:9], v[214:217]
	s_waitcnt vmcnt(6)
	v_mfma_f32_16x16x32_bf16 v[82:85], v[82:85], v[14:17], v[214:217]
	s_waitcnt lgkmcnt(1)
	v_mfma_f32_16x16x32_bf16 v[102:105], v[94:97], v[10:13], v[86:89]
	s_waitcnt vmcnt(5)
	v_mfma_f32_16x16x32_bf16 v[86:89], v[94:97], v[18:21], v[82:85]
	v_mfma_f32_16x16x32_bf16 v[82:85], v[90:93], v[6:9], v[218:221]
	v_mfma_f32_16x16x32_bf16 v[90:93], v[90:93], v[14:17], v[218:221]
	s_waitcnt lgkmcnt(0)
	v_mfma_f32_16x16x32_bf16 v[98:101], v[106:109], v[10:13], v[82:85]
	v_mfma_f32_16x16x32_bf16 v[82:85], v[106:109], v[18:21], v[90:93]
	s_nop 4
	ds_read_b128 v[90:93], v5 offset:4096
	ds_read_b128 v[106:109], v5 offset:6144
	ds_read_b128 v[114:117], v4 offset:4096
	ds_read_b128 v[118:121], v4 offset:6144
	s_waitcnt lgkmcnt(3)
	v_mfma_f32_16x16x32_bf16 v[94:97], v[90:93], v[6:9], v[222:225]
	v_mfma_f32_16x16x32_bf16 v[90:93], v[90:93], v[14:17], v[222:225]
	s_waitcnt lgkmcnt(1)
	v_mfma_f32_16x16x32_bf16 v[110:113], v[114:117], v[10:13], v[94:97]
	v_mfma_f32_16x16x32_bf16 v[94:97], v[114:117], v[18:21], v[90:93]
	v_mfma_f32_16x16x32_bf16 v[90:93], v[106:109], v[6:9], v[226:229]
	v_mfma_f32_16x16x32_bf16 v[114:117], v[106:109], v[14:17], v[226:229]
	s_waitcnt lgkmcnt(0)
	v_mfma_f32_16x16x32_bf16 v[106:109], v[118:121], v[10:13], v[90:93]
	v_mfma_f32_16x16x32_bf16 v[90:93], v[118:121], v[18:21], v[114:117]
	s_cmp_eq_u32 s23, 0
	s_cbranch_scc1 .LBB0_713
	s_xor_b32 s70, s69, 1
	s_lshl_b32 s0, s70, 14
	s_add_i32 s0, s0, 0
	v_add3_u32 v4, s0, v170, v172
	v_add_u32_e32 v5, s0, v171
	s_waitcnt vmcnt(4)
	ds_write_b128 v4, v[58:61]
	s_waitcnt vmcnt(3)
	ds_write_b128 v5, v[62:65] offset:8192
	s_waitcnt vmcnt(2)
	ds_write_b128 v4, v[70:73] offset:4096
	s_waitcnt vmcnt(1)
	ds_write_b128 v5, v[74:77] offset:12288
	s_and_saveexec_b64 s[0:1], s[10:11]
	s_cbranch_execz .LBB0_712
	v_lshl_add_u32 v4, s70, 8, v182
	s_waitcnt vmcnt(0)
	v_xor_b32_e32 v179, 0x80000000, v179
	ds_write_b32 v4, v179 offset:32768

; __device__ __forceinline__ void attn_block(const Params& P, int bh, int qb, unsigned char* smem) {
;     ...
;     auto load_tile = [&](int kv) {
;         const int key0 = kv * 64 + srow0, key1 = key0 + 32;
;         const bf16_t* p0 = z + (size_t)(b * L + (key0 < L ? key0 : L - 1)) * NZ + h * 64 + sch * 8;
;         const bf16_t* p1 = z + (size_t)(b * L + (key1 < L ? key1 : L - 1)) * NZ + h * 64 + sch * 8;
;         rk0 = *(const uint4*)(p0 + ZC_FK); rv0 = *(const uint4*)(p0 + ZC_FV);
;         rk1 = *(const uint4*)(p1 + ZC_FK); rv1 = *(const uint4*)(p1 + ZC_FV);
;         const int keyc = kv * 64 + (tid & 63);
;         rc = cum[keyc < L ? keyc : L - 1];
;     };
.LBB0_713:
	s_cmp_lt_u32 s23, 2
	s_cbranch_scc1 .LBB0_715
	global_load_dwordx4 v[58:61], v198, s[98:99] offset:1024
	global_load_dwordx4 v[62:65], v198, s[98:99] offset:2048
	global_load_dwordx4 v[70:73], v199, s[98:99] offset:1024
	global_load_dwordx4 v[74:77], v199, s[98:99] offset:2048
	v_lshl_add_u32 v4, s43, 2, v242
	s_sub_u32 s98, s98, 0x70000
	s_subb_u32 s99, s99, 0
	global_load_dword v179, v4, s[12:13]

; __device__ __forceinline__ void attn_block(const Params& P, int bh, int qb, unsigned char* smem) {
;     ...
;         f32x4 ck[4];
; #pragma unroll
;         for (int c = 0; c < 4; ++c) ck[c] = *(const f32x4*)(sck + 16 * c + 4 * g);
;         bf16x8 pf[2][2];
; #pragma unroll
;         for (int u = 0; u < 2; ++u) {
;             float mx = -INFINITY;
; #pragma unroll
;             for (int c = 0; c < 4; ++c) {
;                 sa[u][c] -= ck[c];
;                 mx = fmaxf(mx, fmaxf(fmaxf(sa[u][c][0], sa[u][c][1]), fmaxf(sa[u][c][2], sa[u][c][3])));
;             }
;             mx = x4_max(mx);
;             if (__builtin_amdgcn_ballot_w64(mx > m[u]) != 0ull) {
;                 const float mn = fmaxf(m[u], mx);
;                 const float alpha = __builtin_amdgcn_exp2f(m[u] - mn);
;                 m[u] = mn;
; #pragma unroll
;                 for (int c = 0; c < 5; ++c) o[u][c] *= alpha;
;             }
.LBB0_717:
	s_nop 1
	v_max3_f32 v192, v102, v103, v104
	v_max3_f32 v193, v105, v98, v99
	v_max3_f32 v194, v100, v101, v110
	v_max3_f32 v195, v111, v112, v113
	v_max3_f32 v128, v106, v107, v108
	v_max3_f32 v192, v192, v193, v109
	v_max3_f32 v194, v194, v195, v128
	v_max_f32_e32 v192, v192, v194
	v_mov_b32_e32 v193, v192
	s_nop 1
	v_permlane32_swap_b32_e32 v192, v193
	s_nop 1
	v_max_f32_e32 v192, v192, v193
	v_mov_b32_e32 v193, v192
	s_nop 1
	v_permlane16_swap_b32_e32 v192, v193
	s_nop 1
	v_max_f32_e32 v192, v192, v193
	v_cmp_gt_f32_e32 vcc, v192, v187
	s_cbranch_vccz .LBB0_719
	v_max_f32_e32 v193, v187, v192
	v_sub_f32_e32 v192, v187, v193
	v_exp_f32_e32 v192, v192
	v_mov_b32_e32 v187, v193
	v_xor_b32_e32 v196, 0x80000000, v193
	v_pk_mul_f32 v[68:69], v[68:69], v[192:193] op_sel_hi:[1,0]
	v_pk_mul_f32 v[66:67], v[66:67], v[192:193] op_sel_hi:[1,0]
	v_pk_mul_f32 v[52:53], v[52:53], v[192:193] op_sel_hi:[1,0]
	v_pk_mul_f32 v[50:51], v[50:51], v[192:193] op_sel_hi:[1,0]
	v_pk_mul_f32 v[48:49], v[48:49], v[192:193] op_sel_hi:[1,0]
	v_pk_mul_f32 v[46:47], v[46:47], v[192:193] op_sel_hi:[1,0]
	v_pk_mul_f32 v[44:45], v[44:45], v[192:193] op_sel_hi:[1,0]
	v_pk_mul_f32 v[42:43], v[42:43], v[192:193] op_sel_hi:[1,0]
	v_pk_mul_f32 v[80:81], v[80:81], v[192:193] op_sel_hi:[1,0]
	v_pk_mul_f32 v[78:79], v[78:79], v[192:193] op_sel_hi:[1,0]
.LBB0_719:
	v_max3_f32 v192, v86, v87, v88
	v_max3_f32 v193, v89, v82, v83
	v_max3_f32 v194, v84, v85, v94
	v_max3_f32 v195, v95, v96, v97
	v_max3_f32 v128, v90, v91, v92
	v_max3_f32 v192, v192, v193, v93
	v_max3_f32 v194, v194, v195, v128
	v_max_f32_e32 v192, v192, v194
	v_mov_b32_e32 v193, v192
	s_nop 1
	v_permlane32_swap_b32_e32 v192, v193
	s_nop 1
	v_max_f32_e32 v192, v192, v193
	v_mov_b32_e32 v193, v192
	s_nop 1
	v_permlane16_swap_b32_e32 v192, v193
	s_nop 1
	v_max_f32_e32 v192, v192, v193
	v_cmp_gt_f32_e32 vcc, v192, v2
	s_cbranch_vccz .LBB0_708
	v_max_f32_e32 v193, v2, v192
	v_sub_f32_e32 v192, v2, v193
	v_exp_f32_e32 v192, v192
	v_mov_b32_e32 v2, v193
	v_xor_b32_e32 v230, 0x80000000, v193
	v_pk_mul_f32 v[36:37], v[36:37], v[192:193] op_sel_hi:[1,0]
	v_pk_mul_f32 v[34:35], v[34:35], v[192:193] op_sel_hi:[1,0]
	v_pk_mul_f32 v[32:33], v[32:33], v[192:193] op_sel_hi:[1,0]
	v_pk_mul_f32 v[30:31], v[30:31], v[192:193] op_sel_hi:[1,0]
	v_pk_mul_f32 v[28:29], v[28:29], v[192:193] op_sel_hi:[1,0]
	v_pk_mul_f32 v[26:27], v[26:27], v[192:193] op_sel_hi:[1,0]
	v_pk_mul_f32 v[24:25], v[24:25], v[192:193] op_sel_hi:[1,0]
	v_pk_mul_f32 v[22:23], v[22:23], v[192:193] op_sel_hi:[1,0]
	v_pk_mul_f32 v[40:41], v[40:41], v[192:193] op_sel_hi:[1,0]
	v_pk_mul_f32 v[38:39], v[38:39], v[192:193] op_sel_hi:[1,0]
	s_branch .LBB0_708

; __global__ void __launch_bounds__(256, 2) mega(Params P) {
;     extern __shared__ __attribute__((aligned(16))) unsigned char smem[];
	.amdhsa_kernel _ZN12_GLOBAL__N_14megaENS_6ParamsE
		.amdhsa_group_segment_fixed_size 0
		.amdhsa_private_segment_fixed_size 0
		.amdhsa_kernarg_size 408
		.amdhsa_user_sgpr_count 2
		.amdhsa_user_sgpr_dispatch_ptr 0
		.amdhsa_user_sgpr_queue_ptr 0
		.amdhsa_user_sgpr_kernarg_segment_ptr 1
		.amdhsa_user_sgpr_dispatch_id 0
		.amdhsa_user_sgpr_kernarg_preload_length 0
		.amdhsa_user_sgpr_kernarg_preload_offset 0
		.amdhsa_user_sgpr_private_segment_size 0
		.amdhsa_uses_dynamic_stack 0
		.amdhsa_enable_private_segment 0
		.amdhsa_system_sgpr_workgroup_id_x 1
		.amdhsa_system_sgpr_workgroup_id_y 0
		.amdhsa_system_sgpr_workgroup_id_z 0
		.amdhsa_system_sgpr_workgroup_info 0
		.amdhsa_system_vgpr_workitem_id 0
		.amdhsa_next_free_vgpr 256
		.amdhsa_next_free_sgpr 100
		.amdhsa_accum_offset 256
		.amdhsa_reserve_vcc 1
		.amdhsa_float_round_mode_32 0
		.amdhsa_float_round_mode_16_64 0
		.amdhsa_float_denorm_mode_32 3
		.amdhsa_float_denorm_mode_16_64 3
		.amdhsa_dx10_clamp 1
		.amdhsa_ieee_mode 1
		.amdhsa_fp16_overflow 0
		.amdhsa_tg_split 0
		.amdhsa_exception_fp_ieee_invalid_op 0
		.amdhsa_exception_fp_denorm_src 0
		.amdhsa_exception_fp_ieee_div_zero 0
		.amdhsa_exception_fp_ieee_overflow 0
		.amdhsa_exception_fp_ieee_underflow 0
		.amdhsa_exception_fp_ieee_inexact 0
		.amdhsa_exception_int_div_zero 0
	.end_amdhsa_kernel

; __global__ void __launch_bounds__(256, 2) mega(Params P) {
;     extern __shared__ __attribute__((aligned(16))) unsigned char smem[];
amdhsa.kernels:
  - .agpr_count:     0
    .args:
      - .offset:         0
        .size:           152
        .value_kind:     by_value
      - .offset:         152
        .size:           4
        .value_kind:     hidden_block_count_x
      - .offset:         156
        .size:           4
        .value_kind:     hidden_block_count_y
      - .offset:         160
        .size:           4
        .value_kind:     hidden_block_count_z
      - .offset:         164
        .size:           2
        .value_kind:     hidden_group_size_x
      - .offset:         166
        .size:           2
        .value_kind:     hidden_group_size_y
      - .offset:         168
        .size:           2
        .value_kind:     hidden_group_size_z
      - .offset:         170
        .size:           2
        .value_kind:     hidden_remainder_x
      - .offset:         172
        .size:           2
        .value_kind:     hidden_remainder_y
      - .offset:         174
        .size:           2
        .value_kind:     hidden_remainder_z
      - .offset:         192
        .size:           8
        .value_kind:     hidden_global_offset_x
      - .offset:         200
        .size:           8
        .value_kind:     hidden_global_offset_y
      - .offset:         208
        .size:           8
        .value_kind:     hidden_global_offset_z
      - .offset:         216
        .size:           2
        .value_kind:     hidden_grid_dims
      - .offset:         272
        .size:           4
        .value_kind:     hidden_dynamic_lds_size
    .group_segment_fixed_size: 0
    .kernarg_segment_align: 8
    .kernarg_segment_size: 408
    .language:       OpenCL C
    .language_version:
      - 2
      - 0
    .max_flat_workgroup_size: 256
    .name:           _ZN12_GLOBAL__N_14megaENS_6ParamsE
    .private_segment_fixed_size: 0
    .sgpr_count:     106
    .sgpr_spill_count: 84
    .symbol:         _ZN12_GLOBAL__N_14megaENS_6ParamsE.kd
    .uniform_work_group_size: 1
    .uses_dynamic_stack: false
    .vgpr_count:     256
    .vgpr_spill_count: 0
    .wavefront_size: 64
